# counted waits: per-block operand waits in the 6c job loops no longer drain the previous block's output stores, plus conflict-free LDS pitch for staged k rows in 6a; stacked on previous best
# speedup vs baseline: 1.0084x; 1.0084x over previous
; template <int MODE>
; __device__ __forceinline__ void gdn_job(const Params& P, float* lw, int head, int rb, int seg) {
;     ...
;     const int lane = threadIdx.x & 63, jg = lane & 7, ig = lane >> 3, qh = head >> 1;
;     const int ltt = lane >> 3, lc16 = (lane & 7) * 16, lc4 = (lane & 7) * 4;
;     const int row0 = rb * 32 + ig * 4;
;     f32x2 S[4][8];
;     if constexpr (MODE == 2) {
;         const float* sp = (const float*)((const unsigned char*)P.out + 96 * MiB) + ((size_t)(head * NSEG + seg) * 128 + row0) * 128 + jg * 16;
; #pragma unroll
;         for (int ri = 0; ri < 4; ++ri)
; #pragma unroll
;             for (int q4 = 0; q4 < 4; ++q4) { const f32x4 a = *(const f32x4*)(sp + ri * 128 + q4 * 4); S[ri][2 * q4] = (f32x2){a.x, a.y}; S[ri][2 * q4 + 1] = (f32x2){a.z, a.w}; }
;     } else {
; #pragma unroll
;         for (int ri = 0; ri < 4; ++ri)
; #pragma unroll
;             for (int jj = 0; jj < 8; ++jj) { S[ri][jj] = (f32x2){0.f, 0.f}; if (MODE == 0) { if (row0 + ri == jg * 16 + 2 * jj) S[ri][jj].x = 1.f; if (row0 + ri == jg * 16 + 2 * jj + 1) S[ri][jj].y = 1.f; } }
;     }
;     u32x4 g_k0, g_k1, g_q0, g_q1; u32x2 g_v; float g_al = 0.f, g_be = 0.f;
;     const int tbase = seg * SEGLEN;
;     auto issue = [&](int blk) {
;         const int t = tbase + blk * TBK + ltt;
;         const bf16_t* rowp = gp + (size_t)t * 2048;
;         g_k0 = *(const u32x4*)(rowp + 512 + qh * 128 + lc16); g_k1 = *(const u32x4*)(rowp + 512 + qh * 128 + lc16 + 8);
;         if (MODE == 2) { g_q0 = *(const u32x4*)(rowp + qh * 128 + lc16); g_q1 = *(const u32x4*)(rowp + qh * 128 + lc16 + 8); }
;         if (MODE != 0) g_v = *(const u32x2*)(rowp + 1024 + head * 128 + rb * 32 + lc4);
;         if (lane < TBK) { const int tq = tbase + blk * TBK + lane; g_al = gg[tq * 8 + head]; g_be = gbeta[tq * 8 + head]; }
;     };
;     issue(0);
;     for (int blk = 0; blk < SEGLEN / TBK; ++blk) {
;         {
;             float a[8], b[8];
;             UNPK8(a, g_k0); UNPK8(b, g_k1);
;             *(f32x4*)(sk + ltt * 128 + lc16) = (f32x4){a[0], a[1], a[2], a[3]}; *(f32x4*)(sk + ltt * 128 + lc16 + 4) = (f32x4){a[4], a[5], a[6], a[7]};
;             *(f32x4*)(sk + ltt * 128 + lc16 + 8) = (f32x4){b[0], b[1], b[2], b[3]}; *(f32x4*)(sk + ltt * 128 + lc16 + 12) = (f32x4){b[4], b[5], b[6], b[7]};
.LBB0_481:
	s_or_b64 exec, exec, s[6:7]
	s_movk_i32 s6, 0x3000
	v_mad_i32_i24 v136, v189, s6, 0
	s_movk_i32 s6, 0x800
	s_lshl_b32 s42, s28, 3
	v_mul_i32_i24_e32 v133, 0x3000, v189
	v_cmp_gt_i32_e64 s[8:9], s6, v162
	v_bfe_u32 v111, v158, 3, 3
	v_lshrrev_b32_e32 v137, 1, v158
	s_waitcnt lgkmcnt(0)
	s_barrier
	s_and_saveexec_b64 s[10:11], s[8:9]
	s_cbranch_execz .LBB0_532
	s_add_u32 s12, s26, 0x4000000
	s_addc_u32 s13, s27, 0
	s_add_u32 s14, s26, 0x4080000
	v_and_b32_e32 v106, 0x70, v164
	s_addc_u32 s15, s27, 0
	v_mov_b32_e32 v113, 0
	v_lshl_add_u32 v139, v106, 2, v136
	v_and_b32_e32 v220, 64, v106
	v_lshrrev_b32_e32 v220, 2, v220
	v_add_u32_e32 v139, v139, v220
	s_add_u32 s18, s24, 0x4000000
	v_lshlrev_b32_e32 v112, 1, v106
	v_add_u32_e32 v2, 0, v133
	v_and_b32_e32 v138, 28, v137
	v_or_b32_e32 v107, 4, v106
	v_or_b32_e32 v118, 8, v106
	v_or_b32_e32 v119, 12, v106
	v_cmp_gt_u32_e32 vcc, 8, v160
	v_mul_u32_u24_e32 v140, 0x210, v111
	v_add_u32_e32 v140, v140, v139
	v_lshl_add_u32 v141, v160, 2, v136
	s_addc_u32 s19, s25, 0
	v_lshl_add_u64 v[108:109], s[26:27], 0, v[112:113]
	v_add_u32_e32 v142, 0x2400, v2
	s_mov_b64 s[56:57], 0
	v_lshlrev_b32_e32 v114, 1, v106
	v_mov_b32_e32 v115, v113
	s_movk_i32 s40, 0x60
	s_movk_i32 s41, 0x7ff
	v_mov_b32_e32 v120, v162
	s_branch .LBB0_484

; template <int CTRL> __device__ __forceinline__ float dppf(float v) { return __builtin_bit_cast(float, __builtin_amdgcn_update_dpp(0, __builtin_bit_cast(int, v), CTRL, 0xF, 0xF, true)); }
; template <int MODE>
; __device__ __forceinline__ void gdn_job(const Params& P, float* lw, int head, int rb, int seg) {
;     ...
;         for (int s = 0; s < TBK; ++s) {
;             f32x2 k[8], q[8]; f32x4 v = {0.f, 0.f, 0.f, 0.f};
; #pragma unroll
;             for (int q4 = 0; q4 < 4; ++q4) { const f32x4 x = *(const f32x4*)(sk + s * 128 + jg * 16 + q4 * 4); k[2 * q4] = (f32x2){x.x, x.y}; k[2 * q4 + 1] = (f32x2){x.z, x.w}; }
;             if (MODE == 2) {
; #pragma unroll
;                 for (int q4 = 0; q4 < 4; ++q4) { const f32x4 x = *(const f32x4*)(sq + s * 128 + jg * 16 + q4 * 4); q[2 * q4] = (f32x2){x.x, x.y}; q[2 * q4 + 1] = (f32x2){x.z, x.w}; }
;             }
;             if (MODE != 0) v = *(const f32x4*)(sv + s * 32 + ig * 4);
;             const float al = sal[s], be = sbe[s];
;             float ok = 0.f;
;             float sa[4];
; #pragma unroll
;             for (int ri = 0; ri < 4; ++ri) {
;                 f32x2 a2 = S[ri][0] * k[0], a3 = S[ri][1] * k[1];
; #pragma unroll
;                 for (int jj = 2; jj < 8; jj += 2) { a2 += S[ri][jj] * k[jj]; a3 += S[ri][jj + 1] * k[jj + 1]; }
;                 a2 += a3; sa[ri] = a2.x + a2.y;
;             }
; #pragma unroll
;             for (int ri = 0; ri < 4; ++ri) sa[ri] += dppf<0xB1>(sa[ri]);
; #pragma unroll
;             for (int ri = 0; ri < 4; ++ri) sa[ri] += dppf<0x4E>(sa[ri]);
; #pragma unroll
;             for (int ri = 0; ri < 4; ++ri) sa[ri] += dppf<0x141>(sa[ri]);
; #pragma unroll
;             for (int ri = 0; ri < 4; ++ri) {
;                 const float c = (MODE != 0) ? be * (v[ri] - al * sa[ri]) : -be * al * sa[ri];
; #pragma unroll
;                 for (int jj = 0; jj < 8; ++jj) S[ri][jj] = S[ri][jj] * al + k[jj] * c;
;             }
.LBB0_494:
	v_add_u32_e32 v129, s6, v142
	ds_read_b128 v[86:89], v112
	ds_read_b128 v[82:85], v112 offset:16
	ds_read_b128 v[78:81], v112 offset:32
	ds_read_b128 v[74:77], v112 offset:48
	ds_read2_b64 v[144:147], v129 offset1:4
	ds_read_b128 v[90:93], v112 offset:528
	ds_read_b128 v[94:97], v112 offset:544
	ds_read_b128 v[98:101], v112 offset:560
	ds_read_b128 v[102:105], v112 offset:576
	s_waitcnt lgkmcnt(4)
	v_pk_mul_f32 v[134:135], v[70:71], v[86:87]
	v_pk_mul_f32 v[148:149], v[38:39], v[86:87]
	v_pk_mul_f32 v[150:151], v[54:55], v[86:87]
	v_pk_mul_f32 v[152:153], v[50:51], v[86:87]
	v_pk_fma_f32 v[134:135], v[72:73], v[88:89], v[134:135]
	v_pk_fma_f32 v[148:149], v[40:41], v[88:89], v[148:149]
	v_pk_fma_f32 v[150:151], v[56:57], v[88:89], v[150:151]
	v_pk_fma_f32 v[152:153], v[52:53], v[88:89], v[152:153]
	v_pk_fma_f32 v[134:135], v[66:67], v[82:83], v[134:135]
	v_pk_fma_f32 v[148:149], v[34:35], v[82:83], v[148:149]
	v_pk_fma_f32 v[150:151], v[18:19], v[82:83], v[150:151]
	v_pk_fma_f32 v[152:153], v[46:47], v[82:83], v[152:153]
	v_pk_fma_f32 v[134:135], v[68:69], v[84:85], v[134:135]
	v_pk_fma_f32 v[148:149], v[36:37], v[84:85], v[148:149]
	v_pk_fma_f32 v[150:151], v[20:21], v[84:85], v[150:151]
	v_pk_fma_f32 v[152:153], v[48:49], v[84:85], v[152:153]
	v_pk_fma_f32 v[134:135], v[62:63], v[78:79], v[134:135]
	v_pk_fma_f32 v[148:149], v[30:31], v[78:79], v[148:149]
	v_pk_fma_f32 v[150:151], v[14:15], v[78:79], v[150:151]
	v_pk_fma_f32 v[152:153], v[42:43], v[78:79], v[152:153]
	v_pk_fma_f32 v[134:135], v[64:65], v[80:81], v[134:135]
	v_pk_fma_f32 v[148:149], v[32:33], v[80:81], v[148:149]
	v_pk_fma_f32 v[150:151], v[16:17], v[80:81], v[150:151]
	v_pk_fma_f32 v[152:153], v[44:45], v[80:81], v[152:153]
	v_pk_fma_f32 v[134:135], v[58:59], v[74:75], v[134:135]
	v_pk_fma_f32 v[148:149], v[26:27], v[74:75], v[148:149]
	v_pk_fma_f32 v[150:151], v[10:11], v[74:75], v[150:151]
	v_pk_fma_f32 v[152:153], v[22:23], v[74:75], v[152:153]
	v_pk_fma_f32 v[134:135], v[60:61], v[76:77], v[134:135]
	v_pk_fma_f32 v[148:149], v[28:29], v[76:77], v[148:149]
	v_pk_fma_f32 v[150:151], v[12:13], v[76:77], v[150:151]
	v_pk_fma_f32 v[152:153], v[24:25], v[76:77], v[152:153]
	v_add_f32_e32 v134, v134, v135
	v_add_f32_e32 v148, v148, v149
	v_add_f32_e32 v150, v150, v151
	v_add_f32_e32 v152, v152, v153
	v_add_f32_dpp v134, v134, v134 quad_perm:[1,0,3,2] row_mask:0xf bank_mask:0xf bound_ctrl:1
	v_add_f32_dpp v148, v148, v148 quad_perm:[1,0,3,2] row_mask:0xf bank_mask:0xf bound_ctrl:1
	v_add_f32_dpp v150, v150, v150 quad_perm:[1,0,3,2] row_mask:0xf bank_mask:0xf bound_ctrl:1
	v_add_f32_dpp v152, v152, v152 quad_perm:[1,0,3,2] row_mask:0xf bank_mask:0xf bound_ctrl:1
	v_add_f32_dpp v134, v134, v134 quad_perm:[2,3,0,1] row_mask:0xf bank_mask:0xf bound_ctrl:1
	v_add_f32_dpp v148, v148, v148 quad_perm:[2,3,0,1] row_mask:0xf bank_mask:0xf bound_ctrl:1
	v_add_f32_dpp v150, v150, v150 quad_perm:[2,3,0,1] row_mask:0xf bank_mask:0xf bound_ctrl:1
	v_add_f32_dpp v152, v152, v152 quad_perm:[2,3,0,1] row_mask:0xf bank_mask:0xf bound_ctrl:1
	v_add_f32_dpp v134, v134, v134 row_half_mirror row_mask:0xf bank_mask:0xf bound_ctrl:1
	v_add_f32_dpp v148, v148, v148 row_half_mirror row_mask:0xf bank_mask:0xf bound_ctrl:1
	v_add_f32_dpp v150, v150, v150 row_half_mirror row_mask:0xf bank_mask:0xf bound_ctrl:1
	v_add_f32_dpp v152, v152, v152 row_half_mirror row_mask:0xf bank_mask:0xf bound_ctrl:1
	v_mul_f32_e64 v134, v134, -v146
	v_mul_f32_e64 v148, v148, -v146
	v_mul_f32_e64 v150, v150, -v146
	v_mul_f32_e64 v152, v152, -v146
	v_mul_f32_e32 v236, v236, v144
	v_pk_fma_f32 v[70:71], v[86:87], v[134:135], v[70:71] op_sel_hi:[1,0,1]
	v_pk_fma_f32 v[72:73], v[88:89], v[134:135], v[72:73] op_sel_hi:[1,0,1]
	v_pk_fma_f32 v[66:67], v[82:83], v[134:135], v[66:67] op_sel_hi:[1,0,1]
	v_pk_fma_f32 v[68:69], v[84:85], v[134:135], v[68:69] op_sel_hi:[1,0,1]
	v_pk_fma_f32 v[62:63], v[78:79], v[134:135], v[62:63] op_sel_hi:[1,0,1]
	v_pk_fma_f32 v[64:65], v[80:81], v[134:135], v[64:65] op_sel_hi:[1,0,1]
	v_pk_fma_f32 v[58:59], v[74:75], v[134:135], v[58:59] op_sel_hi:[1,0,1]
	v_pk_fma_f32 v[60:61], v[76:77], v[134:135], v[60:61] op_sel_hi:[1,0,1]
	v_pk_fma_f32 v[38:39], v[86:87], v[148:149], v[38:39] op_sel_hi:[1,0,1]
	v_pk_fma_f32 v[40:41], v[88:89], v[148:149], v[40:41] op_sel_hi:[1,0,1]
	v_pk_fma_f32 v[34:35], v[82:83], v[148:149], v[34:35] op_sel_hi:[1,0,1]
	v_pk_fma_f32 v[36:37], v[84:85], v[148:149], v[36:37] op_sel_hi:[1,0,1]
	v_pk_fma_f32 v[30:31], v[78:79], v[148:149], v[30:31] op_sel_hi:[1,0,1]
	v_pk_fma_f32 v[32:33], v[80:81], v[148:149], v[32:33] op_sel_hi:[1,0,1]
	v_pk_fma_f32 v[26:27], v[74:75], v[148:149], v[26:27] op_sel_hi:[1,0,1]
	v_pk_fma_f32 v[28:29], v[76:77], v[148:149], v[28:29] op_sel_hi:[1,0,1]
	v_pk_fma_f32 v[54:55], v[86:87], v[150:151], v[54:55] op_sel_hi:[1,0,1]
	v_pk_fma_f32 v[56:57], v[88:89], v[150:151], v[56:57] op_sel_hi:[1,0,1]
	v_pk_fma_f32 v[18:19], v[82:83], v[150:151], v[18:19] op_sel_hi:[1,0,1]
	v_pk_fma_f32 v[20:21], v[84:85], v[150:151], v[20:21] op_sel_hi:[1,0,1]
	v_pk_fma_f32 v[14:15], v[78:79], v[150:151], v[14:15] op_sel_hi:[1,0,1]
	v_pk_fma_f32 v[16:17], v[80:81], v[150:151], v[16:17] op_sel_hi:[1,0,1]
	v_pk_fma_f32 v[10:11], v[74:75], v[150:151], v[10:11] op_sel_hi:[1,0,1]
	v_pk_fma_f32 v[12:13], v[76:77], v[150:151], v[12:13] op_sel_hi:[1,0,1]
	v_pk_fma_f32 v[50:51], v[86:87], v[152:153], v[50:51] op_sel_hi:[1,0,1]
	v_pk_fma_f32 v[52:53], v[88:89], v[152:153], v[52:53] op_sel_hi:[1,0,1]
	v_pk_fma_f32 v[46:47], v[82:83], v[152:153], v[46:47] op_sel_hi:[1,0,1]
	v_pk_fma_f32 v[48:49], v[84:85], v[152:153], v[48:49] op_sel_hi:[1,0,1]
	v_pk_fma_f32 v[42:43], v[78:79], v[152:153], v[42:43] op_sel_hi:[1,0,1]
	v_pk_fma_f32 v[44:45], v[80:81], v[152:153], v[44:45] op_sel_hi:[1,0,1]
	v_pk_fma_f32 v[22:23], v[74:75], v[152:153], v[22:23] op_sel_hi:[1,0,1]
	v_pk_fma_f32 v[24:25], v[76:77], v[152:153], v[24:25] op_sel_hi:[1,0,1]
	s_waitcnt lgkmcnt(0)
; template <int CTRL> __device__ __forceinline__ float dppf(float v) { return __builtin_bit_cast(float, __builtin_amdgcn_update_dpp(0, __builtin_bit_cast(int, v), CTRL, 0xF, 0xF, true)); }
; template <int MODE>
; __device__ __forceinline__ void gdn_job(const Params& P, float* lw, int head, int rb, int seg) {
;     ...
;             for (int q4 = 0; q4 < 4; ++q4) { const f32x4 x = *(const f32x4*)(sk + s * 128 + jg * 16 + q4 * 4); k[2 * q4] = (f32x2){x.x, x.y}; k[2 * q4 + 1] = (f32x2){x.z, x.w}; }
;             if (MODE == 2) {
; #pragma unroll
;                 for (int q4 = 0; q4 < 4; ++q4) { const f32x4 x = *(const f32x4*)(sq + s * 128 + jg * 16 + q4 * 4); q[2 * q4] = (f32x2){x.x, x.y}; q[2 * q4 + 1] = (f32x2){x.z, x.w}; }
;             }
;             if (MODE != 0) v = *(const f32x4*)(sv + s * 32 + ig * 4);
;             const float al = sal[s], be = sbe[s];
;             float ok = 0.f;
;             float sa[4];
; #pragma unroll
;             for (int ri = 0; ri < 4; ++ri) {
;                 f32x2 a2 = S[ri][0] * k[0], a3 = S[ri][1] * k[1];
; #pragma unroll
;                 for (int jj = 2; jj < 8; jj += 2) { a2 += S[ri][jj] * k[jj]; a3 += S[ri][jj + 1] * k[jj + 1]; }
;                 a2 += a3; sa[ri] = a2.x + a2.y;
;             }
; #pragma unroll
;             for (int ri = 0; ri < 4; ++ri) sa[ri] += dppf<0xB1>(sa[ri]);
; #pragma unroll
;             for (int ri = 0; ri < 4; ++ri) sa[ri] += dppf<0x4E>(sa[ri]);
; #pragma unroll
;             for (int ri = 0; ri < 4; ++ri) sa[ri] += dppf<0x141>(sa[ri]);
; #pragma unroll
;             for (int ri = 0; ri < 4; ++ri) {
;                 const float c = (MODE != 0) ? be * (v[ri] - al * sa[ri]) : -be * al * sa[ri];
; #pragma unroll
;                 for (int jj = 0; jj < 8; ++jj) S[ri][jj] = S[ri][jj] * al + k[jj] * c;
;             }
	v_pk_mul_f32 v[134:135], v[70:71], v[90:91]
	v_pk_mul_f32 v[148:149], v[38:39], v[90:91]
	v_pk_mul_f32 v[150:151], v[54:55], v[90:91]
	v_pk_mul_f32 v[152:153], v[50:51], v[90:91]
	v_pk_fma_f32 v[134:135], v[72:73], v[92:93], v[134:135]
	v_pk_fma_f32 v[148:149], v[40:41], v[92:93], v[148:149]
	v_pk_fma_f32 v[150:151], v[56:57], v[92:93], v[150:151]
	v_pk_fma_f32 v[152:153], v[52:53], v[92:93], v[152:153]
	v_pk_fma_f32 v[134:135], v[66:67], v[94:95], v[134:135]
	v_pk_fma_f32 v[148:149], v[34:35], v[94:95], v[148:149]
	v_pk_fma_f32 v[150:151], v[18:19], v[94:95], v[150:151]
	v_pk_fma_f32 v[152:153], v[46:47], v[94:95], v[152:153]
	v_pk_fma_f32 v[134:135], v[68:69], v[96:97], v[134:135]
	v_pk_fma_f32 v[148:149], v[36:37], v[96:97], v[148:149]
	v_pk_fma_f32 v[150:151], v[20:21], v[96:97], v[150:151]
	v_pk_fma_f32 v[152:153], v[48:49], v[96:97], v[152:153]
	v_pk_fma_f32 v[134:135], v[62:63], v[98:99], v[134:135]
	v_pk_fma_f32 v[148:149], v[30:31], v[98:99], v[148:149]
	v_pk_fma_f32 v[150:151], v[14:15], v[98:99], v[150:151]
	v_pk_fma_f32 v[152:153], v[42:43], v[98:99], v[152:153]
	v_pk_fma_f32 v[134:135], v[64:65], v[100:101], v[134:135]
	v_pk_fma_f32 v[148:149], v[32:33], v[100:101], v[148:149]
	v_pk_fma_f32 v[150:151], v[16:17], v[100:101], v[150:151]
	v_pk_fma_f32 v[152:153], v[44:45], v[100:101], v[152:153]
	v_pk_fma_f32 v[134:135], v[58:59], v[102:103], v[134:135]
	v_pk_fma_f32 v[148:149], v[26:27], v[102:103], v[148:149]
	v_pk_fma_f32 v[150:151], v[10:11], v[102:103], v[150:151]
	v_pk_fma_f32 v[152:153], v[22:23], v[102:103], v[152:153]
	v_pk_fma_f32 v[134:135], v[60:61], v[104:105], v[134:135]
	v_pk_fma_f32 v[148:149], v[28:29], v[104:105], v[148:149]
	v_pk_fma_f32 v[150:151], v[12:13], v[104:105], v[150:151]
	v_pk_fma_f32 v[152:153], v[24:25], v[104:105], v[152:153]
	v_add_f32_e32 v134, v134, v135
	v_add_f32_e32 v148, v148, v149
	v_add_f32_e32 v150, v150, v151
	v_add_f32_e32 v152, v152, v153
	v_add_f32_dpp v134, v134, v134 quad_perm:[1,0,3,2] row_mask:0xf bank_mask:0xf bound_ctrl:1
	v_add_f32_dpp v148, v148, v148 quad_perm:[1,0,3,2] row_mask:0xf bank_mask:0xf bound_ctrl:1
	v_add_f32_dpp v150, v150, v150 quad_perm:[1,0,3,2] row_mask:0xf bank_mask:0xf bound_ctrl:1
	v_add_f32_dpp v152, v152, v152 quad_perm:[1,0,3,2] row_mask:0xf bank_mask:0xf bound_ctrl:1
	v_add_f32_dpp v134, v134, v134 quad_perm:[2,3,0,1] row_mask:0xf bank_mask:0xf bound_ctrl:1
	v_add_f32_dpp v148, v148, v148 quad_perm:[2,3,0,1] row_mask:0xf bank_mask:0xf bound_ctrl:1
	v_add_f32_dpp v150, v150, v150 quad_perm:[2,3,0,1] row_mask:0xf bank_mask:0xf bound_ctrl:1
	v_add_f32_dpp v152, v152, v152 quad_perm:[2,3,0,1] row_mask:0xf bank_mask:0xf bound_ctrl:1
	v_add_f32_dpp v134, v134, v134 row_half_mirror row_mask:0xf bank_mask:0xf bound_ctrl:1
	v_add_f32_dpp v148, v148, v148 row_half_mirror row_mask:0xf bank_mask:0xf bound_ctrl:1
	v_add_f32_dpp v150, v150, v150 row_half_mirror row_mask:0xf bank_mask:0xf bound_ctrl:1
	v_add_f32_dpp v152, v152, v152 row_half_mirror row_mask:0xf bank_mask:0xf bound_ctrl:1
	v_mul_f32_e64 v134, v134, -v147
	v_mul_f32_e64 v148, v148, -v147
	v_mul_f32_e64 v150, v150, -v147
	v_mul_f32_e64 v152, v152, -v147
	v_mul_f32_e32 v236, v236, v145
	v_pk_fma_f32 v[70:71], v[90:91], v[134:135], v[70:71] op_sel_hi:[1,0,1]
	v_pk_fma_f32 v[72:73], v[92:93], v[134:135], v[72:73] op_sel_hi:[1,0,1]
	v_pk_fma_f32 v[66:67], v[94:95], v[134:135], v[66:67] op_sel_hi:[1,0,1]
	v_pk_fma_f32 v[68:69], v[96:97], v[134:135], v[68:69] op_sel_hi:[1,0,1]
	v_pk_fma_f32 v[62:63], v[98:99], v[134:135], v[62:63] op_sel_hi:[1,0,1]
	v_pk_fma_f32 v[64:65], v[100:101], v[134:135], v[64:65] op_sel_hi:[1,0,1]
	v_pk_fma_f32 v[58:59], v[102:103], v[134:135], v[58:59] op_sel_hi:[1,0,1]
	v_pk_fma_f32 v[60:61], v[104:105], v[134:135], v[60:61] op_sel_hi:[1,0,1]
	v_pk_fma_f32 v[38:39], v[90:91], v[148:149], v[38:39] op_sel_hi:[1,0,1]
	v_pk_fma_f32 v[40:41], v[92:93], v[148:149], v[40:41] op_sel_hi:[1,0,1]
	v_pk_fma_f32 v[34:35], v[94:95], v[148:149], v[34:35] op_sel_hi:[1,0,1]
	v_pk_fma_f32 v[36:37], v[96:97], v[148:149], v[36:37] op_sel_hi:[1,0,1]
	v_pk_fma_f32 v[30:31], v[98:99], v[148:149], v[30:31] op_sel_hi:[1,0,1]
	v_pk_fma_f32 v[32:33], v[100:101], v[148:149], v[32:33] op_sel_hi:[1,0,1]
	v_pk_fma_f32 v[26:27], v[102:103], v[148:149], v[26:27] op_sel_hi:[1,0,1]
	v_pk_fma_f32 v[28:29], v[104:105], v[148:149], v[28:29] op_sel_hi:[1,0,1]
	v_pk_fma_f32 v[54:55], v[90:91], v[150:151], v[54:55] op_sel_hi:[1,0,1]
	v_pk_fma_f32 v[56:57], v[92:93], v[150:151], v[56:57] op_sel_hi:[1,0,1]
	v_pk_fma_f32 v[18:19], v[94:95], v[150:151], v[18:19] op_sel_hi:[1,0,1]
	v_pk_fma_f32 v[20:21], v[96:97], v[150:151], v[20:21] op_sel_hi:[1,0,1]
	v_pk_fma_f32 v[14:15], v[98:99], v[150:151], v[14:15] op_sel_hi:[1,0,1]
	v_pk_fma_f32 v[16:17], v[100:101], v[150:151], v[16:17] op_sel_hi:[1,0,1]
	v_pk_fma_f32 v[10:11], v[102:103], v[150:151], v[10:11] op_sel_hi:[1,0,1]
	v_pk_fma_f32 v[12:13], v[104:105], v[150:151], v[12:13] op_sel_hi:[1,0,1]
	v_pk_fma_f32 v[50:51], v[90:91], v[152:153], v[50:51] op_sel_hi:[1,0,1]
	v_pk_fma_f32 v[52:53], v[92:93], v[152:153], v[52:53] op_sel_hi:[1,0,1]
	v_pk_fma_f32 v[46:47], v[94:95], v[152:153], v[46:47] op_sel_hi:[1,0,1]
	v_pk_fma_f32 v[48:49], v[96:97], v[152:153], v[48:49] op_sel_hi:[1,0,1]
	v_pk_fma_f32 v[42:43], v[98:99], v[152:153], v[42:43] op_sel_hi:[1,0,1]
	v_pk_fma_f32 v[44:45], v[100:101], v[152:153], v[44:45] op_sel_hi:[1,0,1]
	v_pk_fma_f32 v[22:23], v[102:103], v[152:153], v[22:23] op_sel_hi:[1,0,1]
	v_pk_fma_f32 v[24:25], v[104:105], v[152:153], v[24:25] op_sel_hi:[1,0,1]
	s_add_i32 s6, s6, 8
	v_add_u32_e32 v112, 0x420, v112
	s_cmp_eq_u32 s6, 32
	s_cbranch_scc0 .LBB0_494
	s_cmp_eq_u32 s43, 32
	s_cbranch_scc1 .LBB0_483
	s_mov_b32 s58, s43
	s_branch .LBB0_487

; template <int CTRL> __device__ __forceinline__ float dppf(float v) { return __builtin_bit_cast(float, __builtin_amdgcn_update_dpp(0, __builtin_bit_cast(int, v), CTRL, 0xF, 0xF, true)); }
; template <int MODE>
; __device__ __forceinline__ void gdn_job(const Params& P, float* lw, int head, int rb, int seg) {
;     ...
;             for (int q4 = 0; q4 < 4; ++q4) { const f32x4 x = *(const f32x4*)(sk + s * 128 + jg * 16 + q4 * 4); k[2 * q4] = (f32x2){x.x, x.y}; k[2 * q4 + 1] = (f32x2){x.z, x.w}; }
;             if (MODE == 2) {
; #pragma unroll
;                 for (int q4 = 0; q4 < 4; ++q4) { const f32x4 x = *(const f32x4*)(sq + s * 128 + jg * 16 + q4 * 4); q[2 * q4] = (f32x2){x.x, x.y}; q[2 * q4 + 1] = (f32x2){x.z, x.w}; }
;             }
;             if (MODE != 0) v = *(const f32x4*)(sv + s * 32 + ig * 4);
;             const float al = sal[s], be = sbe[s];
;             float ok = 0.f;
;             float sa[4];
; #pragma unroll
;             for (int ri = 0; ri < 4; ++ri) {
;                 f32x2 a2 = S[ri][0] * k[0], a3 = S[ri][1] * k[1];
; #pragma unroll
;                 for (int jj = 2; jj < 8; jj += 2) { a2 += S[ri][jj] * k[jj]; a3 += S[ri][jj + 1] * k[jj + 1]; }
;                 a2 += a3; sa[ri] = a2.x + a2.y;
;             }
; #pragma unroll
;             for (int ri = 0; ri < 4; ++ri) sa[ri] += dppf<0xB1>(sa[ri]);
; #pragma unroll
;             for (int ri = 0; ri < 4; ++ri) sa[ri] += dppf<0x4E>(sa[ri]);
; #pragma unroll
;             for (int ri = 0; ri < 4; ++ri) sa[ri] += dppf<0x141>(sa[ri]);
; #pragma unroll
;             for (int ri = 0; ri < 4; ++ri) {
;                 const float c = (MODE != 0) ? be * (v[ri] - al * sa[ri]) : -be * al * sa[ri];
; #pragma unroll
;                 for (int jj = 0; jj < 8; ++jj) S[ri][jj] = S[ri][jj] * al + k[jj] * c;
;             }
.LBB0_509:
	ds_read_b128 v[90:93], v115
	ds_read_b128 v[86:89], v115 offset:16
	ds_read_b128 v[82:85], v115 offset:32
	ds_read_b128 v[78:81], v115 offset:48
	v_add_u32_e32 v119, s6, v144
	ds_read2_b64 v[74:77], v116 offset1:4
	ds_read_b128 v[94:97], v115 offset:528
	ds_read_b128 v[98:101], v115 offset:544
	ds_read_b128 v[102:105], v115 offset:560
	ds_read_b128 v[106:109], v115 offset:576
	s_waitcnt lgkmcnt(7)
	v_pk_mul_f32 v[170:171], v[66:67], v[86:87]
	v_pk_mul_f32 v[172:173], v[68:69], v[88:89]
	v_pk_mul_f32 v[174:175], v[50:51], v[86:87]
	v_pk_mul_f32 v[176:177], v[52:53], v[88:89]
	v_pk_mul_f32 v[178:179], v[26:27], v[86:87]
	v_pk_mul_f32 v[180:181], v[28:29], v[88:89]
	v_pk_mul_f32 v[182:183], v[30:31], v[86:87]
	v_pk_mul_f32 v[184:185], v[32:33], v[88:89]
	v_pk_fma_f32 v[170:171], v[70:71], v[90:91], v[170:171]
	v_pk_fma_f32 v[172:173], v[72:73], v[92:93], v[172:173]
	v_pk_fma_f32 v[174:175], v[54:55], v[90:91], v[174:175]
	v_pk_fma_f32 v[176:177], v[56:57], v[92:93], v[176:177]
	v_pk_fma_f32 v[178:179], v[38:39], v[90:91], v[178:179]
	v_pk_fma_f32 v[180:181], v[40:41], v[92:93], v[180:181]
	v_pk_fma_f32 v[182:183], v[34:35], v[90:91], v[182:183]
	v_pk_fma_f32 v[184:185], v[36:37], v[92:93], v[184:185]
	s_waitcnt lgkmcnt(6)
	v_pk_fma_f32 v[170:171], v[62:63], v[82:83], v[170:171]
	v_pk_fma_f32 v[172:173], v[64:65], v[84:85], v[172:173]
	v_pk_fma_f32 v[174:175], v[46:47], v[82:83], v[174:175]
	v_pk_fma_f32 v[176:177], v[48:49], v[84:85], v[176:177]
	v_pk_fma_f32 v[178:179], v[18:19], v[82:83], v[178:179]
	v_pk_fma_f32 v[180:181], v[20:21], v[84:85], v[180:181]
	v_pk_fma_f32 v[182:183], v[22:23], v[82:83], v[182:183]
	v_pk_fma_f32 v[184:185], v[24:25], v[84:85], v[184:185]
	s_waitcnt lgkmcnt(5)
	v_pk_fma_f32 v[170:171], v[58:59], v[78:79], v[170:171]
	v_pk_fma_f32 v[172:173], v[60:61], v[80:81], v[172:173]
	v_pk_fma_f32 v[174:175], v[42:43], v[78:79], v[174:175]
	v_pk_fma_f32 v[176:177], v[44:45], v[80:81], v[176:177]
	v_pk_fma_f32 v[178:179], v[10:11], v[78:79], v[178:179]
	v_pk_fma_f32 v[180:181], v[12:13], v[80:81], v[180:181]
	v_pk_fma_f32 v[182:183], v[14:15], v[78:79], v[182:183]
	v_pk_fma_f32 v[184:185], v[16:17], v[80:81], v[184:185]
	v_pk_add_f32 v[170:171], v[170:171], v[172:173]
	v_pk_add_f32 v[172:173], v[174:175], v[176:177]
	v_pk_add_f32 v[174:175], v[178:179], v[180:181]
	v_pk_add_f32 v[176:177], v[182:183], v[184:185]
	ds_read_b128 v[154:157], v119
	ds_read_b128 v[166:169], v119 offset:128
	v_add_f32_e32 v119, v170, v171
	v_add_f32_e32 v129, v172, v173
	v_add_f32_e32 v153, v174, v175
	v_add_f32_e32 v159, v176, v177
	v_add_f32_dpp v119, v119, v119 quad_perm:[1,0,3,2] row_mask:0xf bank_mask:0xf bound_ctrl:1
	v_add_f32_dpp v129, v129, v129 quad_perm:[1,0,3,2] row_mask:0xf bank_mask:0xf bound_ctrl:1
	v_add_f32_dpp v153, v153, v153 quad_perm:[1,0,3,2] row_mask:0xf bank_mask:0xf bound_ctrl:1
	v_add_f32_dpp v159, v159, v159 quad_perm:[1,0,3,2] row_mask:0xf bank_mask:0xf bound_ctrl:1
	v_add_f32_dpp v119, v119, v119 quad_perm:[2,3,0,1] row_mask:0xf bank_mask:0xf bound_ctrl:1
	v_add_f32_dpp v129, v129, v129 quad_perm:[2,3,0,1] row_mask:0xf bank_mask:0xf bound_ctrl:1
	v_add_f32_dpp v153, v153, v153 quad_perm:[2,3,0,1] row_mask:0xf bank_mask:0xf bound_ctrl:1
	v_add_f32_dpp v159, v159, v159 quad_perm:[2,3,0,1] row_mask:0xf bank_mask:0xf bound_ctrl:1
	v_add_f32_dpp v119, v119, v119 row_half_mirror row_mask:0xf bank_mask:0xf bound_ctrl:1
	v_add_f32_dpp v129, v129, v129 row_half_mirror row_mask:0xf bank_mask:0xf bound_ctrl:1
	v_add_f32_dpp v153, v153, v153 row_half_mirror row_mask:0xf bank_mask:0xf bound_ctrl:1
	v_add_f32_dpp v159, v159, v159 row_half_mirror row_mask:0xf bank_mask:0xf bound_ctrl:1
	s_waitcnt lgkmcnt(1)
	v_fma_f32 v119, -v74, v119, v154
	v_fma_f32 v129, -v74, v129, v155
	v_fma_f32 v153, -v74, v153, v156
	v_fma_f32 v155, -v74, v159, v157
	v_mul_f32_e32 v154, v76, v119
	v_mul_f32_e32 v156, v76, v129
	v_mul_f32_e32 v170, v76, v153
	v_mul_f32_e32 v76, v76, v155
	v_pk_mul_f32 v[176:177], v[86:87], v[154:155] op_sel_hi:[1,0]
	v_pk_mul_f32 v[178:179], v[88:89], v[154:155] op_sel_hi:[1,0]
	v_pk_mul_f32 v[192:193], v[86:87], v[156:157] op_sel_hi:[1,0]
	v_pk_mul_f32 v[194:195], v[88:89], v[156:157] op_sel_hi:[1,0]
	v_pk_mul_f32 v[206:207], v[86:87], v[170:171] op_sel_hi:[1,0]
	v_pk_mul_f32 v[208:209], v[88:89], v[170:171] op_sel_hi:[1,0]
	v_pk_mul_f32 v[86:87], v[86:87], v[76:77] op_sel_hi:[1,0]
	v_pk_mul_f32 v[88:89], v[88:89], v[76:77] op_sel_hi:[1,0]
	v_pk_mul_f32 v[172:173], v[90:91], v[154:155] op_sel_hi:[1,0]
	v_pk_mul_f32 v[174:175], v[92:93], v[154:155] op_sel_hi:[1,0]
	v_pk_mul_f32 v[180:181], v[82:83], v[154:155] op_sel_hi:[1,0]
	v_pk_mul_f32 v[182:183], v[84:85], v[154:155] op_sel_hi:[1,0]
	v_pk_mul_f32 v[184:185], v[78:79], v[154:155] op_sel_hi:[1,0]
	v_pk_mul_f32 v[154:155], v[80:81], v[154:155] op_sel_hi:[1,0]
	v_pk_mul_f32 v[186:187], v[90:91], v[156:157] op_sel_hi:[1,0]
	v_pk_mul_f32 v[190:191], v[92:93], v[156:157] op_sel_hi:[1,0]
	v_pk_mul_f32 v[196:197], v[82:83], v[156:157] op_sel_hi:[1,0]
	v_pk_mul_f32 v[198:199], v[84:85], v[156:157] op_sel_hi:[1,0]
	v_pk_mul_f32 v[200:201], v[78:79], v[156:157] op_sel_hi:[1,0]
	v_pk_mul_f32 v[156:157], v[80:81], v[156:157] op_sel_hi:[1,0]
	v_pk_mul_f32 v[202:203], v[90:91], v[170:171] op_sel_hi:[1,0]
	v_pk_mul_f32 v[204:205], v[92:93], v[170:171] op_sel_hi:[1,0]
	v_pk_mul_f32 v[210:211], v[82:83], v[170:171] op_sel_hi:[1,0]
	v_pk_mul_f32 v[212:213], v[84:85], v[170:171] op_sel_hi:[1,0]
	v_pk_mul_f32 v[214:215], v[78:79], v[170:171] op_sel_hi:[1,0]
	v_pk_mul_f32 v[170:171], v[80:81], v[170:171] op_sel_hi:[1,0]
	v_pk_mul_f32 v[90:91], v[90:91], v[76:77] op_sel_hi:[1,0]
; template <int CTRL> __device__ __forceinline__ float dppf(float v) { return __builtin_bit_cast(float, __builtin_amdgcn_update_dpp(0, __builtin_bit_cast(int, v), CTRL, 0xF, 0xF, true)); }
; template <int MODE>
; __device__ __forceinline__ void gdn_job(const Params& P, float* lw, int head, int rb, int seg) {
;     ...
;             for (int ri = 0; ri < 4; ++ri) {
;                 f32x2 a2 = S[ri][0] * k[0], a3 = S[ri][1] * k[1];
; #pragma unroll
;                 for (int jj = 2; jj < 8; jj += 2) { a2 += S[ri][jj] * k[jj]; a3 += S[ri][jj + 1] * k[jj + 1]; }
;                 a2 += a3; sa[ri] = a2.x + a2.y;
;             }
; #pragma unroll
;             for (int ri = 0; ri < 4; ++ri) sa[ri] += dppf<0xB1>(sa[ri]);
; #pragma unroll
;             for (int ri = 0; ri < 4; ++ri) sa[ri] += dppf<0x4E>(sa[ri]);
; #pragma unroll
;             for (int ri = 0; ri < 4; ++ri) sa[ri] += dppf<0x141>(sa[ri]);
; #pragma unroll
;             for (int ri = 0; ri < 4; ++ri) {
;                 const float c = (MODE != 0) ? be * (v[ri] - al * sa[ri]) : -be * al * sa[ri];
; #pragma unroll
;                 for (int jj = 0; jj < 8; ++jj) S[ri][jj] = S[ri][jj] * al + k[jj] * c;
;             }
	v_pk_mul_f32 v[92:93], v[92:93], v[76:77] op_sel_hi:[1,0]
	v_pk_mul_f32 v[82:83], v[82:83], v[76:77] op_sel_hi:[1,0]
	v_pk_mul_f32 v[84:85], v[84:85], v[76:77] op_sel_hi:[1,0]
	v_pk_mul_f32 v[78:79], v[78:79], v[76:77] op_sel_hi:[1,0]
	v_pk_mul_f32 v[80:81], v[80:81], v[76:77] op_sel_hi:[1,0]
	v_pk_fma_f32 v[66:67], v[66:67], v[74:75], v[176:177] op_sel_hi:[1,0,1]
	v_pk_fma_f32 v[68:69], v[68:69], v[74:75], v[178:179] op_sel_hi:[1,0,1]
	v_pk_fma_f32 v[50:51], v[50:51], v[74:75], v[192:193] op_sel_hi:[1,0,1]
	v_pk_fma_f32 v[52:53], v[52:53], v[74:75], v[194:195] op_sel_hi:[1,0,1]
	v_pk_fma_f32 v[26:27], v[26:27], v[74:75], v[206:207] op_sel_hi:[1,0,1]
	v_pk_fma_f32 v[28:29], v[28:29], v[74:75], v[208:209] op_sel_hi:[1,0,1]
	v_pk_fma_f32 v[30:31], v[30:31], v[74:75], v[86:87] op_sel_hi:[1,0,1]
	v_pk_fma_f32 v[32:33], v[32:33], v[74:75], v[88:89] op_sel_hi:[1,0,1]
	v_pk_fma_f32 v[70:71], v[70:71], v[74:75], v[172:173] op_sel_hi:[1,0,1]
	v_pk_fma_f32 v[72:73], v[72:73], v[74:75], v[174:175] op_sel_hi:[1,0,1]
	v_pk_fma_f32 v[54:55], v[54:55], v[74:75], v[186:187] op_sel_hi:[1,0,1]
	v_pk_fma_f32 v[56:57], v[56:57], v[74:75], v[190:191] op_sel_hi:[1,0,1]
	v_pk_fma_f32 v[38:39], v[38:39], v[74:75], v[202:203] op_sel_hi:[1,0,1]
	v_pk_fma_f32 v[40:41], v[40:41], v[74:75], v[204:205] op_sel_hi:[1,0,1]
	v_pk_fma_f32 v[34:35], v[34:35], v[74:75], v[90:91] op_sel_hi:[1,0,1]
	v_pk_fma_f32 v[36:37], v[36:37], v[74:75], v[92:93] op_sel_hi:[1,0,1]
	v_pk_fma_f32 v[22:23], v[22:23], v[74:75], v[82:83] op_sel_hi:[1,0,1]
	v_pk_fma_f32 v[24:25], v[24:25], v[74:75], v[84:85] op_sel_hi:[1,0,1]
	v_pk_fma_f32 v[14:15], v[14:15], v[74:75], v[78:79] op_sel_hi:[1,0,1]
	v_pk_fma_f32 v[16:17], v[16:17], v[74:75], v[80:81] op_sel_hi:[1,0,1]
	v_pk_mul_f32 v[78:79], v[66:67], v[98:99]
	v_pk_mul_f32 v[80:81], v[68:69], v[100:101]
	v_pk_mul_f32 v[82:83], v[50:51], v[98:99]
	v_pk_mul_f32 v[84:85], v[52:53], v[100:101]
	v_pk_mul_f32 v[86:87], v[26:27], v[98:99]
	v_pk_mul_f32 v[88:89], v[28:29], v[100:101]
	v_pk_mul_f32 v[90:91], v[30:31], v[98:99]
	v_pk_mul_f32 v[92:93], v[32:33], v[100:101]
	v_pk_fma_f32 v[62:63], v[62:63], v[74:75], v[180:181] op_sel_hi:[1,0,1]
	v_pk_fma_f32 v[64:65], v[64:65], v[74:75], v[182:183] op_sel_hi:[1,0,1]
	v_pk_fma_f32 v[46:47], v[46:47], v[74:75], v[196:197] op_sel_hi:[1,0,1]
	v_pk_fma_f32 v[48:49], v[48:49], v[74:75], v[198:199] op_sel_hi:[1,0,1]
	v_pk_fma_f32 v[18:19], v[18:19], v[74:75], v[210:211] op_sel_hi:[1,0,1]
	v_pk_fma_f32 v[20:21], v[20:21], v[74:75], v[212:213] op_sel_hi:[1,0,1]
	v_pk_fma_f32 v[78:79], v[70:71], v[94:95], v[78:79]
	v_pk_fma_f32 v[80:81], v[72:73], v[96:97], v[80:81]
	v_pk_fma_f32 v[82:83], v[54:55], v[94:95], v[82:83]
	v_pk_fma_f32 v[84:85], v[56:57], v[96:97], v[84:85]
	v_pk_fma_f32 v[86:87], v[38:39], v[94:95], v[86:87]
	v_pk_fma_f32 v[88:89], v[40:41], v[96:97], v[88:89]
	v_pk_fma_f32 v[90:91], v[34:35], v[94:95], v[90:91]
	v_pk_fma_f32 v[92:93], v[36:37], v[96:97], v[92:93]
	v_pk_fma_f32 v[58:59], v[58:59], v[74:75], v[184:185] op_sel_hi:[1,0,1]
	v_pk_fma_f32 v[60:61], v[60:61], v[74:75], v[154:155] op_sel_hi:[1,0,1]
	v_pk_fma_f32 v[42:43], v[42:43], v[74:75], v[200:201] op_sel_hi:[1,0,1]
	v_pk_fma_f32 v[44:45], v[44:45], v[74:75], v[156:157] op_sel_hi:[1,0,1]
	v_pk_fma_f32 v[10:11], v[10:11], v[74:75], v[214:215] op_sel_hi:[1,0,1]
	v_pk_fma_f32 v[12:13], v[12:13], v[74:75], v[170:171] op_sel_hi:[1,0,1]
	v_pk_fma_f32 v[78:79], v[62:63], v[102:103], v[78:79]
	v_pk_fma_f32 v[80:81], v[64:65], v[104:105], v[80:81]
	v_pk_fma_f32 v[82:83], v[46:47], v[102:103], v[82:83]
	v_pk_fma_f32 v[84:85], v[48:49], v[104:105], v[84:85]
	v_pk_fma_f32 v[86:87], v[18:19], v[102:103], v[86:87]
	v_pk_fma_f32 v[88:89], v[20:21], v[104:105], v[88:89]
	v_pk_fma_f32 v[90:91], v[22:23], v[102:103], v[90:91]
	v_pk_fma_f32 v[92:93], v[24:25], v[104:105], v[92:93]
	v_pk_fma_f32 v[78:79], v[58:59], v[106:107], v[78:79]
	v_pk_fma_f32 v[80:81], v[60:61], v[108:109], v[80:81]
	v_pk_fma_f32 v[82:83], v[42:43], v[106:107], v[82:83]
	v_pk_fma_f32 v[84:85], v[44:45], v[108:109], v[84:85]
	v_pk_fma_f32 v[86:87], v[10:11], v[106:107], v[86:87]
	v_pk_fma_f32 v[88:89], v[12:13], v[108:109], v[88:89]
	v_pk_fma_f32 v[90:91], v[14:15], v[106:107], v[90:91]
	v_pk_fma_f32 v[92:93], v[16:17], v[108:109], v[92:93]
	v_pk_add_f32 v[78:79], v[78:79], v[80:81]
	v_pk_add_f32 v[80:81], v[82:83], v[84:85]
	v_pk_add_f32 v[82:83], v[86:87], v[88:89]
	v_pk_add_f32 v[84:85], v[90:91], v[92:93]
	v_add_f32_e32 v76, v78, v79
	v_add_f32_e32 v78, v80, v81
	v_add_f32_e32 v79, v82, v83
	v_add_f32_e32 v80, v84, v85
	v_add_f32_dpp v76, v76, v76 quad_perm:[1,0,3,2] row_mask:0xf bank_mask:0xf bound_ctrl:1
	v_add_f32_dpp v78, v78, v78 quad_perm:[1,0,3,2] row_mask:0xf bank_mask:0xf bound_ctrl:1
	v_add_f32_dpp v79, v79, v79 quad_perm:[1,0,3,2] row_mask:0xf bank_mask:0xf bound_ctrl:1
	v_add_f32_dpp v80, v80, v80 quad_perm:[1,0,3,2] row_mask:0xf bank_mask:0xf bound_ctrl:1
	v_add_f32_dpp v76, v76, v76 quad_perm:[2,3,0,1] row_mask:0xf bank_mask:0xf bound_ctrl:1
	v_add_f32_dpp v78, v78, v78 quad_perm:[2,3,0,1] row_mask:0xf bank_mask:0xf bound_ctrl:1
	v_add_f32_dpp v79, v79, v79 quad_perm:[2,3,0,1] row_mask:0xf bank_mask:0xf bound_ctrl:1
	v_add_f32_dpp v80, v80, v80 quad_perm:[2,3,0,1] row_mask:0xf bank_mask:0xf bound_ctrl:1
	v_add_f32_dpp v76, v76, v76 row_half_mirror row_mask:0xf bank_mask:0xf bound_ctrl:1
	v_add_f32_dpp v78, v78, v78 row_half_mirror row_mask:0xf bank_mask:0xf bound_ctrl:1
	v_add_f32_dpp v79, v79, v79 row_half_mirror row_mask:0xf bank_mask:0xf bound_ctrl:1
	v_add_f32_dpp v80, v80, v80 row_half_mirror row_mask:0xf bank_mask:0xf bound_ctrl:1
	s_waitcnt lgkmcnt(0)
; template <int CTRL> __device__ __forceinline__ float dppf(float v) { return __builtin_bit_cast(float, __builtin_amdgcn_update_dpp(0, __builtin_bit_cast(int, v), CTRL, 0xF, 0xF, true)); }
; template <int MODE>
; __device__ __forceinline__ void gdn_job(const Params& P, float* lw, int head, int rb, int seg) {
;     ...
;             const float al = sal[s], be = sbe[s];
;             float ok = 0.f;
;             float sa[4];
; #pragma unroll
;             for (int ri = 0; ri < 4; ++ri) {
;                 f32x2 a2 = S[ri][0] * k[0], a3 = S[ri][1] * k[1];
; #pragma unroll
;                 for (int jj = 2; jj < 8; jj += 2) { a2 += S[ri][jj] * k[jj]; a3 += S[ri][jj + 1] * k[jj + 1]; }
;                 a2 += a3; sa[ri] = a2.x + a2.y;
;             }
; #pragma unroll
;             for (int ri = 0; ri < 4; ++ri) sa[ri] += dppf<0xB1>(sa[ri]);
; #pragma unroll
;             for (int ri = 0; ri < 4; ++ri) sa[ri] += dppf<0x4E>(sa[ri]);
; #pragma unroll
;             for (int ri = 0; ri < 4; ++ri) sa[ri] += dppf<0x141>(sa[ri]);
; #pragma unroll
;             for (int ri = 0; ri < 4; ++ri) {
;                 const float c = (MODE != 0) ? be * (v[ri] - al * sa[ri]) : -be * al * sa[ri];
; #pragma unroll
;                 for (int jj = 0; jj < 8; ++jj) S[ri][jj] = S[ri][jj] * al + k[jj] * c;
;             }
	v_fma_f32 v76, -v75, v76, v166
	v_fma_f32 v78, -v75, v78, v167
	v_fma_f32 v79, -v75, v79, v168
	v_fma_f32 v81, -v75, v80, v169
	v_mul_f32_e32 v76, v77, v76
	v_mul_f32_e32 v78, v77, v78
	v_mul_f32_e32 v80, v77, v79
	v_mul_f32_e32 v82, v77, v81
	s_addk_i32 s6, 0x100
	v_pk_mul_f32 v[84:85], v[94:95], v[76:77] op_sel_hi:[1,0]
	v_pk_mul_f32 v[86:87], v[96:97], v[76:77] op_sel_hi:[1,0]
	v_pk_mul_f32 v[88:89], v[98:99], v[76:77] op_sel_hi:[1,0]
	v_pk_mul_f32 v[90:91], v[100:101], v[76:77] op_sel_hi:[1,0]
	v_pk_mul_f32 v[92:93], v[102:103], v[76:77] op_sel_hi:[1,0]
	v_pk_mul_f32 v[154:155], v[104:105], v[76:77] op_sel_hi:[1,0]
	v_pk_mul_f32 v[156:157], v[106:107], v[76:77] op_sel_hi:[1,0]
	v_pk_mul_f32 v[76:77], v[108:109], v[76:77] op_sel_hi:[1,0]
	v_pk_mul_f32 v[166:167], v[94:95], v[78:79] op_sel_hi:[1,0]
	v_pk_mul_f32 v[168:169], v[96:97], v[78:79] op_sel_hi:[1,0]
	v_pk_mul_f32 v[170:171], v[98:99], v[78:79] op_sel_hi:[1,0]
	v_pk_mul_f32 v[172:173], v[100:101], v[78:79] op_sel_hi:[1,0]
	v_pk_mul_f32 v[174:175], v[102:103], v[78:79] op_sel_hi:[1,0]
	v_pk_mul_f32 v[176:177], v[104:105], v[78:79] op_sel_hi:[1,0]
	v_pk_mul_f32 v[178:179], v[106:107], v[78:79] op_sel_hi:[1,0]
	v_pk_mul_f32 v[78:79], v[108:109], v[78:79] op_sel_hi:[1,0]
	v_pk_mul_f32 v[180:181], v[94:95], v[80:81] op_sel_hi:[1,0]
	v_pk_mul_f32 v[182:183], v[96:97], v[80:81] op_sel_hi:[1,0]
	v_pk_mul_f32 v[184:185], v[98:99], v[80:81] op_sel_hi:[1,0]
	v_pk_mul_f32 v[186:187], v[100:101], v[80:81] op_sel_hi:[1,0]
	v_pk_mul_f32 v[190:191], v[102:103], v[80:81] op_sel_hi:[1,0]
	v_pk_mul_f32 v[192:193], v[104:105], v[80:81] op_sel_hi:[1,0]
	v_pk_mul_f32 v[194:195], v[106:107], v[80:81] op_sel_hi:[1,0]
	v_pk_mul_f32 v[80:81], v[108:109], v[80:81] op_sel_hi:[1,0]
	v_pk_mul_f32 v[94:95], v[94:95], v[82:83] op_sel_hi:[1,0]
	v_pk_mul_f32 v[96:97], v[96:97], v[82:83] op_sel_hi:[1,0]
	v_pk_mul_f32 v[98:99], v[98:99], v[82:83] op_sel_hi:[1,0]
	v_pk_mul_f32 v[100:101], v[100:101], v[82:83] op_sel_hi:[1,0]
	v_pk_mul_f32 v[102:103], v[102:103], v[82:83] op_sel_hi:[1,0]
	v_pk_mul_f32 v[104:105], v[104:105], v[82:83] op_sel_hi:[1,0]
	v_pk_mul_f32 v[106:107], v[106:107], v[82:83] op_sel_hi:[1,0]
	v_pk_mul_f32 v[82:83], v[108:109], v[82:83] op_sel_hi:[1,0]
	v_add_u32_e32 v116, 8, v116
	v_add_u32_e32 v115, 0x420, v115
	s_cmpk_eq_i32 s6, 0x400
	v_pk_fma_f32 v[70:71], v[70:71], v[74:75], v[84:85] op_sel:[0,1,0]
	v_pk_fma_f32 v[72:73], v[72:73], v[74:75], v[86:87] op_sel:[0,1,0]
	v_pk_fma_f32 v[66:67], v[66:67], v[74:75], v[88:89] op_sel:[0,1,0]
	v_pk_fma_f32 v[68:69], v[68:69], v[74:75], v[90:91] op_sel:[0,1,0]
	v_pk_fma_f32 v[62:63], v[62:63], v[74:75], v[92:93] op_sel:[0,1,0]
	v_pk_fma_f32 v[64:65], v[64:65], v[74:75], v[154:155] op_sel:[0,1,0]
	v_pk_fma_f32 v[58:59], v[58:59], v[74:75], v[156:157] op_sel:[0,1,0]
	v_pk_fma_f32 v[60:61], v[60:61], v[74:75], v[76:77] op_sel:[0,1,0]
	v_pk_fma_f32 v[54:55], v[54:55], v[74:75], v[166:167] op_sel:[0,1,0]
	v_pk_fma_f32 v[56:57], v[56:57], v[74:75], v[168:169] op_sel:[0,1,0]
	v_pk_fma_f32 v[50:51], v[50:51], v[74:75], v[170:171] op_sel:[0,1,0]
	v_pk_fma_f32 v[52:53], v[52:53], v[74:75], v[172:173] op_sel:[0,1,0]
	v_pk_fma_f32 v[46:47], v[46:47], v[74:75], v[174:175] op_sel:[0,1,0]
	v_pk_fma_f32 v[48:49], v[48:49], v[74:75], v[176:177] op_sel:[0,1,0]
	v_pk_fma_f32 v[42:43], v[42:43], v[74:75], v[178:179] op_sel:[0,1,0]
	v_pk_fma_f32 v[44:45], v[44:45], v[74:75], v[78:79] op_sel:[0,1,0]
	v_pk_fma_f32 v[38:39], v[38:39], v[74:75], v[180:181] op_sel:[0,1,0]
	v_pk_fma_f32 v[40:41], v[40:41], v[74:75], v[182:183] op_sel:[0,1,0]
	v_pk_fma_f32 v[26:27], v[26:27], v[74:75], v[184:185] op_sel:[0,1,0]
	v_pk_fma_f32 v[28:29], v[28:29], v[74:75], v[186:187] op_sel:[0,1,0]
	v_pk_fma_f32 v[18:19], v[18:19], v[74:75], v[190:191] op_sel:[0,1,0]
	v_pk_fma_f32 v[20:21], v[20:21], v[74:75], v[192:193] op_sel:[0,1,0]
	v_pk_fma_f32 v[10:11], v[10:11], v[74:75], v[194:195] op_sel:[0,1,0]
	v_pk_fma_f32 v[12:13], v[12:13], v[74:75], v[80:81] op_sel:[0,1,0]
	v_pk_fma_f32 v[34:35], v[34:35], v[74:75], v[94:95] op_sel:[0,1,0]
	v_pk_fma_f32 v[36:37], v[36:37], v[74:75], v[96:97] op_sel:[0,1,0]
	v_pk_fma_f32 v[30:31], v[30:31], v[74:75], v[98:99] op_sel:[0,1,0]
	v_pk_fma_f32 v[32:33], v[32:33], v[74:75], v[100:101] op_sel:[0,1,0]
	v_pk_fma_f32 v[22:23], v[22:23], v[74:75], v[102:103] op_sel:[0,1,0]
	v_pk_fma_f32 v[24:25], v[24:25], v[74:75], v[104:105] op_sel:[0,1,0]
	v_pk_fma_f32 v[14:15], v[14:15], v[74:75], v[106:107] op_sel:[0,1,0]
	v_pk_fma_f32 v[16:17], v[16:17], v[74:75], v[82:83] op_sel:[0,1,0]
	s_cbranch_scc0 .LBB0_509
	s_cmp_eq_u32 s41, 32
	s_cbranch_scc1 .LBB0_498
	s_mov_b32 s43, s41
	s_branch .LBB0_502

; __device__ __forceinline__ bf16_t f2bf(float f) { return (bf16_t)(cvt_pk_bf16(f, 0.f) & 0xffffu); }
; template <int MODE>
; __device__ __forceinline__ void gdn_job(const Params& P, float* lw, int head, int rb, int seg) {
;     ...
;     const int tbase = seg * SEGLEN;
;     auto issue = [&](int blk) {
;         const int t = tbase + blk * TBK + ltt;
;         const bf16_t* rowp = gp + (size_t)t * 2048;
;         g_k0 = *(const u32x4*)(rowp + 512 + qh * 128 + lc16); g_k1 = *(const u32x4*)(rowp + 512 + qh * 128 + lc16 + 8);
;         if (MODE == 2) { g_q0 = *(const u32x4*)(rowp + qh * 128 + lc16); g_q1 = *(const u32x4*)(rowp + qh * 128 + lc16 + 8); }
;         if (MODE != 0) g_v = *(const u32x2*)(rowp + 1024 + head * 128 + rb * 32 + lc4);
;         if (lane < TBK) { const int tq = tbase + blk * TBK + lane; g_al = gg[tq * 8 + head]; g_be = gbeta[tq * 8 + head]; }
;     };
;     issue(0);
;     for (int blk = 0; blk < SEGLEN / TBK; ++blk) {
;     ...
;             if (MODE == 2) { if (jg < 4) proj[(size_t)(tbase + blk * TBK + s) * PLD + PC_GQKV + head * 128 + row0 + jg] = f2bf(ok); }
.LBB0_659:
	s_or_b64 exec, exec, s[66:67]
	v_and_b32_e32 v95, 1, v95
	v_lshlrev_b32_e32 v95, 7, v95
	v_lshlrev_b32_e32 v106, 1, v119
	v_lshlrev_b32_e32 v91, 7, v91
	v_and_b32_e32 v108, 0xc0, v106
	v_and_or_b32 v106, v91, s41, v95
	v_lshrrev_b32_e32 v84, 3, v120
	v_ashrrev_i32_e32 v107, 31, v106
	v_lshlrev_b64 v[106:107], 1, v[106:107]
	v_and_b32_e32 v84, 63, v84
	v_lshlrev_b32_e32 v103, 1, v113
	v_mad_u64_u32 v[106:107], s[66:67], v84, s43, v[106:107]
	v_or3_b32 v106, v108, v103, v106
	v_lshl_add_u64 v[106:107], v[86:87], 0, v[106:107]
	s_mov_b32 s68, 0
	s_waitcnt vmcnt(0)
	s_branch .LBB0_661

; __device__ __forceinline__ float bflo(unsigned u) { return __uint_as_float(u << 16); }
; __device__ __forceinline__ float bfhi(unsigned u) { return __uint_as_float(u & 0xffff0000u); }
; #define UNPK8(dst, u) do { dst[0] = bflo(u.x); dst[1] = bfhi(u.x); dst[2] = bflo(u.y); dst[3] = bfhi(u.y); dst[4] = bflo(u.z); dst[5] = bfhi(u.z); dst[6] = bflo(u.w); dst[7] = bfhi(u.w); } while (0)
; template <int MODE>
; __device__ __forceinline__ void gdn_job(const Params& P, float* lw, int head, int rb, int seg) {
;     ...
;     for (int blk = 0; blk < SEGLEN / TBK; ++blk) {
;         {
;             float a[8], b[8];
;             UNPK8(a, g_k0); UNPK8(b, g_k1);
;             *(f32x4*)(sk + ltt * 128 + lc16) = (f32x4){a[0], a[1], a[2], a[3]}; *(f32x4*)(sk + ltt * 128 + lc16 + 4) = (f32x4){a[4], a[5], a[6], a[7]};
;             *(f32x4*)(sk + ltt * 128 + lc16 + 8) = (f32x4){b[0], b[1], b[2], b[3]}; *(f32x4*)(sk + ltt * 128 + lc16 + 12) = (f32x4){b[4], b[5], b[6], b[7]};
;             if (MODE == 2) {
;                 UNPK8(a, g_q0); UNPK8(b, g_q1);
;                 *(f32x4*)(sq + ltt * 128 + lc16) = (f32x4){a[0], a[1], a[2], a[3]}; *(f32x4*)(sq + ltt * 128 + lc16 + 4) = (f32x4){a[4], a[5], a[6], a[7]};
;                 *(f32x4*)(sq + ltt * 128 + lc16 + 8) = (f32x4){b[0], b[1], b[2], b[3]}; *(f32x4*)(sq + ltt * 128 + lc16 + 12) = (f32x4){b[4], b[5], b[6], b[7]};
;             }
;             if (MODE != 0) *(f32x4*)(sv + ltt * 32 + lc4) = (f32x4){bflo(g_v.x), bfhi(g_v.x), bflo(g_v.y), bfhi(g_v.y)};
;             if (lane < TBK) { sal[lane] = __expf(g_al); sbe[lane] = g_be; }
.LBB0_661:
	s_waitcnt vmcnt(11)
	v_lshlrev_b32_e32 v126, 16, v6
	v_and_b32_e32 v127, 0xffff0000, v6
	v_lshlrev_b32_e32 v128, 16, v7
	v_and_b32_e32 v129, 0xffff0000, v7
	v_lshlrev_b32_e32 v138, 16, v8
	v_and_b32_e32 v139, 0xffff0000, v8
	v_lshlrev_b32_e32 v140, 16, v9
	v_and_b32_e32 v141, 0xffff0000, v9
	v_lshlrev_b32_e32 v142, 16, v2
	v_and_b32_e32 v143, 0xffff0000, v2
	v_lshlrev_b32_e32 v144, 16, v3
	v_and_b32_e32 v145, 0xffff0000, v3
	v_lshlrev_b32_e32 v146, 16, v4
	v_and_b32_e32 v147, 0xffff0000, v4
	v_lshlrev_b32_e32 v148, 16, v5
	v_and_b32_e32 v149, 0xffff0000, v5
	ds_write_b128 v114, v[126:129]
	ds_write_b128 v114, v[138:141] offset:16
	ds_write_b128 v114, v[142:145] offset:32
	ds_write_b128 v114, v[146:149] offset:48
	s_waitcnt vmcnt(9)
	v_lshlrev_b32_e32 v126, 16, v14
	v_and_b32_e32 v127, 0xffff0000, v14
	v_lshlrev_b32_e32 v128, 16, v15
	v_and_b32_e32 v129, 0xffff0000, v15
	v_lshlrev_b32_e32 v138, 16, v16
	v_and_b32_e32 v139, 0xffff0000, v16
	v_lshlrev_b32_e32 v140, 16, v17
	v_and_b32_e32 v141, 0xffff0000, v17
	v_lshlrev_b32_e32 v142, 16, v10
	v_and_b32_e32 v143, 0xffff0000, v10
	v_lshlrev_b32_e32 v144, 16, v11
	v_and_b32_e32 v145, 0xffff0000, v11
	v_lshlrev_b32_e32 v146, 16, v12
	v_and_b32_e32 v147, 0xffff0000, v12
	v_lshlrev_b32_e32 v148, 16, v13
	v_and_b32_e32 v149, 0xffff0000, v13
	ds_write_b128 v114, v[126:129] offset:4096
	ds_write_b128 v114, v[138:141] offset:4112
	ds_write_b128 v114, v[142:145] offset:4128
	ds_write_b128 v114, v[146:149] offset:4144
	s_waitcnt vmcnt(8)
	v_lshlrev_b32_e32 v126, 16, v104
	v_and_b32_e32 v127, 0xffff0000, v104
	v_lshlrev_b32_e32 v128, 16, v105
	v_and_b32_e32 v129, 0xffff0000, v105
	ds_write_b128 v115, v[126:129] offset:8192
	s_and_saveexec_b64 s[66:67], s[18:19]
	s_cbranch_execz .LBB0_663
	v_mul_f32_e32 v84, 0x3fb8aa3b, v124
	v_exp_f32_e32 v84, v84
	ds_write2_b32 v118, v84, v125 offset1:8

; template <int MODE, int RI>
; __device__ __forceinline__ void rwkv_job(const Params& P, float* lw, int head, int seg, int half) {
;     ...
;     const int tbase = seg * SEGLEN;
;     auto issue = [&](int blk) {
;         const int t = tbase + blk * TBK + ltt;
;         const size_t o = (size_t)t * 1024 + ch;
;         g_ld = *(const u32x4*)(i_ld + o); g_kk = *(const u32x4*)(i_kk + o); g_aa = *(const u32x4*)(i_aa + o);
;         if (MODE != 0) {
;             g_kp = *(const u32x4*)(i_kp + o);
;             g_vc = *(const u32x4*)(proj + (size_t)t * PLD + PC_V + ch);
;             if (t > 0) g_vp = *(const u32x4*)(proj + (size_t)(t - 1) * PLD + PC_V + ch); else g_vp = (u32x4){0u, 0u, 0u, 0u};
;         }
;         if (MODE == 2) {
;             g_rc = *(const u32x4*)(proj + (size_t)t * PLD + PC_R + ch);
;             if (t > 0) g_rp = *(const u32x4*)(proj + (size_t)(t - 1) * PLD + PC_R + ch); else g_rp = (u32x4){0u, 0u, 0u, 0u};
;         }
;     };
;     issue(0);
;     for (int blk = 0; blk < SEGLEN / TBK; ++blk) {
;     ...
;                 for (int e = 0; e < 8; ++e) { sk[o + e] = kp[e]; sv[o + e] = vc[e] + (vp[e] - vc[e]) * mu[2048 + ch + e]; }
;     ...
;                 for (int e = 0; e < 8; ++e) sr[o + e] = rc[e] + (rp[e] - rc[e]) * mu[ch + e];
.LBB0_679:
	s_or_b64 exec, exec, s[78:79]
	v_lshl_add_u64 v[4:5], v[94:95], 2, s[56:57]
	v_add_co_u32_e32 v38, vcc, s81, v4
	v_lshl_add_u64 v[42:43], v[4:5], 0, s[72:73]
	s_nop 0
	v_addc_co_u32_e32 v39, vcc, 0, v5, vcc
	global_load_dwordx4 v[38:41], v[38:39], off
	s_nop 0
	global_load_dwordx4 v[42:45], v[42:43], off offset:16
	s_nop 0
	global_load_dwordx4 v[46:49], v[4:5], off offset:16
	global_load_dwordx4 v[50:53], v[4:5], off
	v_ashrrev_i32_e32 v97, 31, v96
	v_bfe_u32 v2, v110, 5, 1
	v_lshlrev_b32_e32 v4, 1, v87
	v_lshlrev_b64 v[96:97], 1, v[96:97]
	v_and_b32_e32 v98, 63, v98
	v_lshl_add_u32 v105, v2, 7, v102
	v_lshl_or_b32 v2, v2, 6, v4
	v_mad_u64_u32 v[96:97], s[18:19], v98, s82, v[96:97]
	v_lshl_add_u64 v[96:97], v[96:97], 0, v[2:3]
	v_lshl_add_u64 v[4:5], v[94:95], 1, s[64:65]
	s_mov_b32 s78, 0
	v_lshl_add_u64 v[96:97], v[88:89], 0, v[96:97]
	s_waitcnt vmcnt(0)
	s_branch .LBB0_681

; #define UNPK8(dst, u) do { dst[0] = bflo(u.x); dst[1] = bfhi(u.x); dst[2] = bflo(u.y); dst[3] = bfhi(u.y); dst[4] = bflo(u.z); dst[5] = bfhi(u.z); dst[6] = bflo(u.w); dst[7] = bfhi(u.w); } while (0)
; template <int MODE, int RI>
; __device__ __forceinline__ void rwkv_job(const Params& P, float* lw, int head, int seg, int half) {
;     ...
;     auto issue = [&](int blk) {
;         const int t = tbase + blk * TBK + ltt;
;         const size_t o = (size_t)t * 1024 + ch;
;         g_ld = *(const u32x4*)(i_ld + o); g_kk = *(const u32x4*)(i_kk + o); g_aa = *(const u32x4*)(i_aa + o);
;         if (MODE != 0) {
;             g_kp = *(const u32x4*)(i_kp + o);
;             g_vc = *(const u32x4*)(proj + (size_t)t * PLD + PC_V + ch);
;             if (t > 0) g_vp = *(const u32x4*)(proj + (size_t)(t - 1) * PLD + PC_V + ch); else g_vp = (u32x4){0u, 0u, 0u, 0u};
;         }
;         if (MODE == 2) {
;             g_rc = *(const u32x4*)(proj + (size_t)t * PLD + PC_R + ch);
;             if (t > 0) g_rp = *(const u32x4*)(proj + (size_t)(t - 1) * PLD + PC_R + ch); else g_rp = (u32x4){0u, 0u, 0u, 0u};
;         }
;     };
;     issue(0);
;     for (int blk = 0; blk < SEGLEN / TBK; ++blk) {
;         {
;             float ld[8], kk[8], aa[8];
;             UNPK8(ld, g_ld); UNPK8(kk, g_kk); UNPK8(aa, g_aa);
;             const int o = ltt * 64 + lc8;
; #pragma unroll
;             for (int e = 0; e < 8; ++e) { sw[o + e] = __expf(ld[e]); sna[o + e] = -kk[e]; sb[o + e] = kk[e] * aa[e]; }
;             if (MODE != 0) {
;                 float kp[8], vc[8], vp[8];
;                 UNPK8(kp, g_kp); UNPK8(vc, g_vc); UNPK8(vp, g_vp);
; #pragma unroll
;                 for (int e = 0; e < 8; ++e) { sk[o + e] = kp[e]; sv[o + e] = vc[e] + (vp[e] - vc[e]) * mu[2048 + ch + e]; }
;             }
;             if (MODE == 2) {
;                 float rc[8], rp[8];
;                 UNPK8(rc, g_rc); UNPK8(rp, g_rp);
; #pragma unroll
;                 for (int e = 0; e < 8; ++e) sr[o + e] = rc[e] + (rp[e] - rc[e]) * mu[ch + e];
;             }
;         }
;         if (blk + 1 < SEGLEN / TBK) issue(blk + 1);
.LBB0_681:
	s_waitcnt vmcnt(15)
	v_lshlrev_b32_e32 v2, 16, v6
	v_and_b32_e32 v98, 0xffff0000, v6
	v_mul_f32_e32 v2, 0x3fb8aa3b, v2
	v_lshlrev_b32_e32 v108, 16, v7
	v_exp_f32_e32 v106, v2
	v_mul_f32_e32 v2, 0x3fb8aa3b, v98
	v_and_b32_e32 v109, 0xffff0000, v7
	v_exp_f32_e32 v107, v2
	v_mul_f32_e32 v2, 0x3fb8aa3b, v108
	v_exp_f32_e32 v108, v2
	v_mul_f32_e32 v2, 0x3fb8aa3b, v109
	v_exp_f32_e32 v109, v2
	v_lshlrev_b32_e32 v120, 16, v8
	s_waitcnt vmcnt(14)
	v_lshlrev_b32_e32 v98, 16, v10
	v_and_b32_e32 v99, 0xffff0000, v10
	s_waitcnt vmcnt(13)
	v_lshlrev_b32_e32 v114, 16, v14
	v_and_b32_e32 v115, 0xffff0000, v14
	v_and_b32_e32 v121, 0xffff0000, v8
	v_xor_b32_e32 v113, 0x80000000, v99
	v_xor_b32_e32 v112, 0x80000000, v98
	v_pk_mul_f32 v[116:117], v[98:99], v[114:115]
	ds_write_b128 v101, v[106:109] offset:2048
	v_lshlrev_b32_e32 v98, 16, v11
	v_and_b32_e32 v99, 0xffff0000, v11
	v_lshlrev_b32_e32 v106, 16, v15
	v_and_b32_e32 v107, 0xffff0000, v15
	v_mul_f32_e32 v2, 0x3fb8aa3b, v120
	v_lshlrev_b32_e32 v122, 16, v9
	v_pk_mul_f32 v[118:119], v[98:99], v[106:107]
	v_exp_f32_e32 v106, v2
	v_mul_f32_e32 v2, 0x3fb8aa3b, v121
	v_and_b32_e32 v123, 0xffff0000, v9
	v_exp_f32_e32 v107, v2
	v_mul_f32_e32 v2, 0x3fb8aa3b, v122
	v_exp_f32_e32 v108, v2
	v_mul_f32_e32 v2, 0x3fb8aa3b, v123
	v_exp_f32_e32 v109, v2
	v_xor_b32_e32 v115, 0x80000000, v99
	v_xor_b32_e32 v114, 0x80000000, v98
	ds_write_b128 v101, v[112:115] offset:8192
	v_lshlrev_b32_e32 v98, 16, v12
	v_and_b32_e32 v99, 0xffff0000, v12
	v_lshlrev_b32_e32 v114, 16, v16
	v_and_b32_e32 v115, 0xffff0000, v16
	ds_write_b128 v101, v[116:119] offset:10240
	v_xor_b32_e32 v113, 0x80000000, v99
	v_xor_b32_e32 v112, 0x80000000, v98
	v_pk_mul_f32 v[116:117], v[98:99], v[114:115]
	ds_write_b128 v101, v[106:109] offset:2064
	v_lshlrev_b32_e32 v98, 16, v13
	v_and_b32_e32 v99, 0xffff0000, v13
	v_lshlrev_b32_e32 v106, 16, v17
	v_and_b32_e32 v107, 0xffff0000, v17
	v_xor_b32_e32 v115, 0x80000000, v99
	v_xor_b32_e32 v114, 0x80000000, v98
	v_pk_mul_f32 v[118:119], v[98:99], v[106:107]
	s_waitcnt vmcnt(11)
	v_lshlrev_b32_e32 v98, 16, v22
	v_and_b32_e32 v99, 0xffff0000, v22
	s_waitcnt vmcnt(9)
	v_lshlrev_b32_e32 v106, 16, v26
	v_and_b32_e32 v107, 0xffff0000, v26
	v_pk_add_f32 v[106:107], v[106:107], v[98:99] neg_lo:[0,1] neg_hi:[0,1]
	v_lshlrev_b32_e32 v108, 16, v27
	s_waitcnt vmcnt(11)
	v_pk_fma_f32 v[106:107], v[106:107], v[38:39], v[98:99]
	v_lshlrev_b32_e32 v98, 16, v23
	v_and_b32_e32 v99, 0xffff0000, v23
	v_and_b32_e32 v109, 0xffff0000, v27
	v_pk_add_f32 v[108:109], v[108:109], v[98:99] neg_lo:[0,1] neg_hi:[0,1]
	s_mov_b32 s18, s78
	v_pk_fma_f32 v[108:109], v[108:109], v[40:41], v[98:99]
	ds_write_b128 v101, v[106:109] offset:6144
	v_lshlrev_b32_e32 v98, 16, v24
	v_and_b32_e32 v99, 0xffff0000, v24
	v_lshlrev_b32_e32 v106, 16, v28
	v_and_b32_e32 v107, 0xffff0000, v28
	v_pk_add_f32 v[106:107], v[106:107], v[98:99] neg_lo:[0,1] neg_hi:[0,1]
	v_lshlrev_b32_e32 v108, 16, v29
	s_waitcnt vmcnt(10)
	v_pk_fma_f32 v[106:107], v[106:107], v[42:43], v[98:99]
	v_lshlrev_b32_e32 v98, 16, v25
	v_and_b32_e32 v99, 0xffff0000, v25
	v_and_b32_e32 v109, 0xffff0000, v29
	v_pk_add_f32 v[108:109], v[108:109], v[98:99] neg_lo:[0,1] neg_hi:[0,1]
	ds_write_b128 v101, v[112:115] offset:8208
	v_pk_fma_f32 v[108:109], v[108:109], v[44:45], v[98:99]
	ds_write_b128 v101, v[106:109] offset:6160
	v_lshlrev_b32_e32 v98, 16, v30
	v_and_b32_e32 v99, 0xffff0000, v30
	s_waitcnt vmcnt(8)
	v_lshlrev_b32_e32 v106, 16, v34
	v_and_b32_e32 v107, 0xffff0000, v34
	v_pk_add_f32 v[106:107], v[106:107], v[98:99] neg_lo:[0,1] neg_hi:[0,1]
	v_lshlrev_b32_e32 v108, 16, v35
	s_waitcnt vmcnt(8)
	v_pk_fma_f32 v[106:107], v[106:107], v[50:51], v[98:99]
	v_lshlrev_b32_e32 v98, 16, v31
	v_and_b32_e32 v99, 0xffff0000, v31
	v_and_b32_e32 v109, 0xffff0000, v35
	v_pk_add_f32 v[108:109], v[108:109], v[98:99] neg_lo:[0,1] neg_hi:[0,1]
	v_lshlrev_b32_e32 v114, 16, v19
	v_pk_fma_f32 v[108:109], v[108:109], v[52:53], v[98:99]
	ds_write_b128 v101, v[106:109]
	v_lshlrev_b32_e32 v98, 16, v32
	v_and_b32_e32 v99, 0xffff0000, v32
	v_lshlrev_b32_e32 v106, 16, v36
	v_and_b32_e32 v107, 0xffff0000, v36
	v_pk_add_f32 v[106:107], v[106:107], v[98:99] neg_lo:[0,1] neg_hi:[0,1]
	v_lshlrev_b32_e32 v108, 16, v37
	v_pk_fma_f32 v[106:107], v[106:107], v[46:47], v[98:99]
	v_lshlrev_b32_e32 v98, 16, v33
	v_and_b32_e32 v99, 0xffff0000, v33
	v_and_b32_e32 v109, 0xffff0000, v37
	v_lshlrev_b32_e32 v112, 16, v18
	v_and_b32_e32 v115, 0xffff0000, v19
	v_and_b32_e32 v113, 0xffff0000, v18
	v_pk_add_f32 v[108:109], v[108:109], v[98:99] neg_lo:[0,1] neg_hi:[0,1]
	s_add_i32 s78, s78, 1
	ds_write_b128 v101, v[112:115] offset:4096
	v_lshlrev_b32_e32 v114, 16, v21
	v_lshlrev_b32_e32 v112, 16, v20
	v_and_b32_e32 v115, 0xffff0000, v21
	v_and_b32_e32 v113, 0xffff0000, v20
	v_pk_fma_f32 v[108:109], v[108:109], v[48:49], v[98:99]
	s_cmp_eq_u32 s18, 31
	ds_write_b128 v101, v[116:119] offset:10256
	ds_write_b128 v101, v[112:115] offset:4112
	ds_write_b128 v101, v[106:109] offset:16
	s_cbranch_scc1 .LBB0_683
	v_lshl_add_u32 v2, s78, 3, v104
	v_mov_b64_e32 v[22:23], s[64:65]
	v_mad_u64_u32 v[24:25], s[18:19], v2, s43, v[22:23]
	v_lshlrev_b64 v[26:27], 1, v[94:95]
	v_lshlrev_b64 v[6:7], 10, v[2:3]
	v_lshl_add_u64 v[28:29], v[24:25], 0, v[26:27]
	v_add_u32_e32 v2, -1, v2
	v_add_co_u32_e32 v24, vcc, s80, v28
	v_mad_u64_u32 v[22:23], s[18:19], v2, s43, v[22:23]
	v_lshl_add_u64 v[6:7], v[6:7], 0, v[94:95]
	v_addc_co_u32_e32 v25, vcc, 0, v29, vcc
	v_lshl_add_u64 v[22:23], v[22:23], 0, v[26:27]
	v_lshlrev_b64 v[14:15], 1, v[6:7]
	v_add_co_u32_e32 v26, vcc, 0x1000, v22
	v_lshl_add_u64 v[6:7], s[58:59], 0, v[14:15]
	v_lshl_add_u64 v[10:11], s[60:61], 0, v[14:15]
	v_lshl_add_u64 v[16:17], s[68:69], 0, v[14:15]
	v_lshl_add_u64 v[18:19], s[66:67], 0, v[14:15]
	v_addc_co_u32_e32 v27, vcc, 0, v23, vcc
	v_mad_u64_u32 v[34:35], s[18:19], v2, s43, v[4:5]
	global_load_dwordx4 v[6:9], v[6:7], off
	s_nop 0
	global_load_dwordx4 v[10:13], v[10:11], off
	s_nop 0
	global_load_dwordx4 v[14:17], v[16:17], off
	s_nop 0
	global_load_dwordx4 v[18:21], v[18:19], off
	s_nop 0
	global_load_dwordx4 v[22:25], v[24:25], off
	s_nop 0
	global_load_dwordx4 v[30:33], v[28:29], off
	s_nop 0
	global_load_dwordx4 v[26:29], v[26:27], off
	s_nop 0
	global_load_dwordx4 v[34:37], v[34:35], off
